# EVENB item epilogue: its 8 gate and gain loads issued at item start ahead of the next-item prefetch, epilogue left load-free
# baseline (speedup 1.0000x reference)
.LBB0_580:
	s_or_b64 exec, exec, s[4:5]
	v_add_u32_e32 v0, s7, v93
	v_mov_b64_e32 v[2:3], s[12:13]
	v_mad_i64_i32 v[2:3], s[4:5], v0, s85, v[2:3]
	s_lshl_b32 s26, s16, 1
	v_lshl_add_u64 v[2:3], v[2:3], 0, s[26:27]
	v_mov_b32_e32 v87, v169
	v_lshl_add_u64 v[24:25], v[2:3], 0, v[86:87]
	v_add_co_u32_e64 v2, s[4:5], s86, v24
	s_waitcnt vmcnt(0) lgkmcnt(0)
	s_barrier
	s_nop 0
	v_addc_co_u32_e64 v3, s[4:5], 0, v25, s[4:5]
	v_mov_b32_e32 v20, v220
	v_mov_b32_e32 v21, v221
	s_waitcnt lgkmcnt(0)
	v_ashrrev_i32_e32 v1, 31, v0
	v_lshlrev_b64 v[0:1], 11, v[0:1]
	v_lshl_add_u64 v[0:1], s[10:11], 0, v[0:1]
	v_lshl_add_u64 v[28:29], v[0:1], 0, s[26:27]
	s_lshl_b32 s26, s16, 2
	v_lshl_add_u64 v[8:9], v[82:83], 0, s[26:27]
	v_mov_b32_e32 v0, v156
	v_mov_b32_e32 v1, v157
	v_mov_b32_e32 v2, v158
	v_mov_b32_e32 v3, v159
	v_add_u32_e32 v22, s14, v88
	ds_read2st64_b32 v[22:23], v22 offset0:204 offset1:205
	ds_read_b32 v34, v96 offset:52224
	ds_read_b32 v35, v97 offset:52224
	s_mov_b64 s[4:5], 0x1800
	v_lshl_add_u64 v[26:27], v[24:25], 0, s[4:5]
	v_lshl_add_u64 v[24:25], v[28:29], 0, v[86:87]
	v_mov_b32_e32 v30, v222
	v_mov_b32_e32 v31, v223
	v_mov_b32_e32 v28, v224
	v_mov_b32_e32 v29, v225
	s_waitcnt lgkmcnt(0)
	v_pk_add_f32 v[22:23], v[22:23], v[34:35]
	s_mov_b32 s7, 0xf700000
	v_add_f32_e32 v22, v22, v23
	v_fmamk_f32 v22, v22, 0x3c000000, v226
	v_rsq_f32_e32 v22, v22
	v_add_co_u32_e64 v34, s[4:5], s7, v24
	s_add_i32 s6, s6, s24
	v_pk_mul_f32 v[32:33], v[32:33], v[22:23] op_sel_hi:[1,0]
	v_pk_mul_f32 v[18:19], v[18:19], v[22:23] op_sel_hi:[1,0]
	v_addc_co_u32_e64 v35, s[4:5], 0, v25, s[4:5]
	s_mov_b64 s[4:5], 0xf700400
	s_add_i32 s15, s15, s76
	s_cmpk_gt_i32 s6, 0x3ff
	v_lshl_add_u64 v[84:85], v[84:85], 0, s[34:35]
	v_lshlrev_b32_e32 v36, 16, v20
	v_and_b32_e32 v37, 0xffff0000, v20
	v_lshlrev_b32_e32 v20, 16, v21
	v_and_b32_e32 v21, 0xffff0000, v21
	v_mul_f32_e32 v23, 0xbfb8aa3b, v36
	v_mul_f32_e32 v38, 0xbfb8aa3b, v37
	v_mul_f32_e32 v39, 0xbfb8aa3b, v20
	v_mul_f32_e32 v40, 0xbfb8aa3b, v21
	v_exp_f32_e32 v23, v23
	v_exp_f32_e32 v38, v38
	v_exp_f32_e32 v39, v39
	v_exp_f32_e32 v40, v40
	v_add_f32_e32 v23, 1.0, v23
	v_add_f32_e32 v41, 1.0, v38
	v_add_f32_e32 v42, 1.0, v39
	v_add_f32_e32 v43, 1.0, v40
	v_rcp_f32_e32 v38, v23
	v_rcp_f32_e32 v39, v41
	v_rcp_f32_e32 v40, v42
	v_rcp_f32_e32 v41, v43
	v_pk_mul_f32 v[0:1], v[0:1], v[32:33]
	v_pk_mul_f32 v[2:3], v[2:3], v[18:19]
	v_pk_mul_f32 v[18:19], v[38:39], v[36:37]
	v_pk_mul_f32 v[20:21], v[40:41], v[20:21]
	v_pk_mul_f32 v[0:1], v[0:1], v[18:19]
	v_pk_mul_f32 v[2:3], v[2:3], v[20:21]
	v_cvt_pk_bf16_f32 v0, v0, v1
	v_cvt_pk_bf16_f32 v1, v2, v3
	global_store_dwordx2 v[34:35], v[0:1], off offset:1024
	v_mov_b32_e32 v18, v160
	v_mov_b32_e32 v19, v161
	v_mov_b32_e32 v20, v162
	v_mov_b32_e32 v21, v163
	v_mov_b32_e32 v2, v228
	v_mov_b32_e32 v3, v229
	v_lshl_add_u64 v[0:1], v[24:25], 0, s[4:5]
	v_lshlrev_b32_e32 v24, 16, v30
	v_and_b32_e32 v25, 0xffff0000, v30
	v_lshlrev_b32_e32 v26, 16, v31
	v_and_b32_e32 v27, 0xffff0000, v31
	v_mul_f32_e32 v23, 0xbfb8aa3b, v24
	v_mul_f32_e32 v30, 0xbfb8aa3b, v25
	v_mul_f32_e32 v31, 0xbfb8aa3b, v26
	v_mul_f32_e32 v32, 0xbfb8aa3b, v27
	v_exp_f32_e32 v23, v23
	v_exp_f32_e32 v30, v30
	v_exp_f32_e32 v31, v31
	v_exp_f32_e32 v32, v32
	v_add_f32_e32 v23, 1.0, v23
	v_add_f32_e32 v33, 1.0, v30
	v_add_f32_e32 v34, 1.0, v31
	v_add_f32_e32 v35, 1.0, v32
	v_rcp_f32_e32 v30, v23
	v_rcp_f32_e32 v31, v33
	v_rcp_f32_e32 v32, v34
	v_rcp_f32_e32 v33, v35
	v_pk_mul_f32 v[14:15], v[14:15], v[22:23] op_sel_hi:[1,0]
	v_pk_mul_f32 v[16:17], v[16:17], v[22:23] op_sel_hi:[1,0]
	v_pk_mul_f32 v[24:25], v[30:31], v[24:25]
	v_pk_mul_f32 v[26:27], v[32:33], v[26:27]
	v_pk_mul_f32 v[14:15], v[14:15], v[18:19]
	v_pk_mul_f32 v[16:17], v[16:17], v[20:21]
	v_pk_mul_f32 v[14:15], v[14:15], v[24:25]
	v_pk_mul_f32 v[16:17], v[16:17], v[26:27]
	v_cvt_pk_bf16_f32 v14, v14, v15
	v_cvt_pk_bf16_f32 v15, v16, v17
	global_store_dwordx2 v[0:1], v[14:15], off offset:16
	v_mov_b32_e32 v14, v164
	v_mov_b32_e32 v15, v165
	v_mov_b32_e32 v16, v166
	v_mov_b32_e32 v17, v167
	v_lshlrev_b32_e32 v18, 16, v2
	v_and_b32_e32 v19, 0xffff0000, v2
	v_lshlrev_b32_e32 v2, 16, v3
	v_and_b32_e32 v3, 0xffff0000, v3
	v_mul_f32_e32 v20, 0xbfb8aa3b, v18
	v_mul_f32_e32 v21, 0xbfb8aa3b, v19
	v_mul_f32_e32 v23, 0xbfb8aa3b, v2
	v_mul_f32_e32 v24, 0xbfb8aa3b, v3
	v_exp_f32_e32 v20, v20
	v_exp_f32_e32 v21, v21
	v_exp_f32_e32 v23, v23
	v_exp_f32_e32 v24, v24
	v_add_f32_e32 v20, 1.0, v20
	v_add_f32_e32 v21, 1.0, v21
	v_add_f32_e32 v23, 1.0, v23
	v_add_f32_e32 v25, 1.0, v24
	v_rcp_f32_e32 v20, v20
	v_rcp_f32_e32 v21, v21
	v_rcp_f32_e32 v24, v23
	v_rcp_f32_e32 v25, v25
	v_pk_mul_f32 v[10:11], v[10:11], v[22:23] op_sel_hi:[1,0]
	v_pk_mul_f32 v[12:13], v[12:13], v[22:23] op_sel_hi:[1,0]
	v_pk_mul_f32 v[18:19], v[20:21], v[18:19]
	v_pk_mul_f32 v[2:3], v[24:25], v[2:3]
	v_pk_mul_f32 v[4:5], v[4:5], v[22:23] op_sel_hi:[1,0]
	v_pk_mul_f32 v[6:7], v[6:7], v[22:23] op_sel_hi:[1,0]
	v_pk_mul_f32 v[10:11], v[10:11], v[14:15]
	v_pk_mul_f32 v[12:13], v[12:13], v[16:17]
	v_pk_mul_f32 v[10:11], v[10:11], v[18:19]
	v_pk_mul_f32 v[2:3], v[12:13], v[2:3]
	v_cvt_pk_bf16_f32 v10, v10, v11
	v_cvt_pk_bf16_f32 v11, v2, v3
	global_store_dwordx2 v[0:1], v[10:11], off offset:32
	v_mov_b32_e32 v8, v216
	v_mov_b32_e32 v9, v217
	v_mov_b32_e32 v10, v218
	v_mov_b32_e32 v11, v219
	v_lshlrev_b32_e32 v2, 16, v28
	v_and_b32_e32 v3, 0xffff0000, v28
	v_lshlrev_b32_e32 v12, 16, v29
	v_and_b32_e32 v13, 0xffff0000, v29
	v_mul_f32_e32 v14, 0xbfb8aa3b, v2
	v_mul_f32_e32 v15, 0xbfb8aa3b, v3
	v_mul_f32_e32 v16, 0xbfb8aa3b, v12
	v_mul_f32_e32 v17, 0xbfb8aa3b, v13
	v_exp_f32_e32 v14, v14
	v_exp_f32_e32 v15, v15
	v_exp_f32_e32 v16, v16
	v_exp_f32_e32 v17, v17
	v_add_f32_e32 v14, 1.0, v14
	v_add_f32_e32 v15, 1.0, v15
	v_add_f32_e32 v16, 1.0, v16
	v_add_f32_e32 v17, 1.0, v17
	v_rcp_f32_e32 v14, v14
	v_rcp_f32_e32 v15, v15
	v_rcp_f32_e32 v16, v16
	v_rcp_f32_e32 v17, v17
	v_pk_mul_f32 v[2:3], v[14:15], v[2:3]
	v_pk_mul_f32 v[12:13], v[16:17], v[12:13]
	v_pk_mul_f32 v[4:5], v[4:5], v[8:9]
	v_pk_mul_f32 v[6:7], v[6:7], v[10:11]
	v_pk_mul_f32 v[2:3], v[4:5], v[2:3]
	v_pk_mul_f32 v[4:5], v[6:7], v[12:13]
	v_cvt_pk_bf16_f32 v2, v2, v3
	v_cvt_pk_bf16_f32 v3, v4, v5
	global_store_dwordx2 v[0:1], v[2:3], off offset:48
	s_waitcnt lgkmcnt(0)
	s_barrier
	s_cbranch_scc1 .LBB0_583
.LBB0_581:
	s_and_b32 s7, s15, 0xffffffc0
	s_and_b32 s16, s6, 3
	s_getpc_b64 s[4:5]
	s_add_u32 s4, s4, _ZN2mk5LOG2GE@rel32@lo+4
	s_addc_u32 s5, s5, _ZN2mk5LOG2GE@rel32@hi+12
	s_lshl_b32 s17, s16, 2
	s_load_dword s4, s[4:5], s17 offset:0x0
	s_lshl_b32 s16, s16, 7
	s_waitcnt vmcnt(4)
	v_mov_b32_e32 v0, v176
	v_mov_b32_e32 v1, v177
	v_mov_b32_e32 v2, v178
	v_mov_b32_e32 v3, v179
	v_mov_b32_e32 v4, v180
	v_mov_b32_e32 v5, v181
	v_mov_b32_e32 v6, v182
	v_mov_b32_e32 v7, v183
	v_mov_b32_e32 v8, v184
	v_mov_b32_e32 v9, v185
	v_mov_b32_e32 v10, v186
	v_mov_b32_e32 v11, v187
	v_mov_b32_e32 v12, v188
	v_mov_b32_e32 v13, v189
	v_mov_b32_e32 v14, v190
	v_mov_b32_e32 v15, v191
	v_mov_b32_e32 v16, v192
	v_mov_b32_e32 v17, v193
	v_mov_b32_e32 v18, v194
	v_mov_b32_e32 v19, v195
	v_mov_b32_e32 v20, v196
	v_mov_b32_e32 v21, v197
	v_mov_b32_e32 v22, v198
	v_mov_b32_e32 v23, v199
	v_mov_b32_e32 v24, v200
	v_mov_b32_e32 v25, v201
	v_mov_b32_e32 v26, v202
	v_mov_b32_e32 v27, v203
	v_mov_b32_e32 v28, v204
	v_mov_b32_e32 v29, v205
	v_mov_b32_e32 v30, v206
	v_mov_b32_e32 v31, v207
	v_mov_b32_e32 v32, v208
	v_mov_b32_e32 v33, v209
	v_mov_b32_e32 v34, v210
	v_mov_b32_e32 v35, v211
	v_mov_b32_e32 v36, v212
	v_mov_b32_e32 v37, v213
	v_mov_b32_e32 v38, v214
	v_mov_b32_e32 v39, v215
	v_add_u32_e32 v234, s7, v93
	v_mov_b64_e32 v[236:237], s[12:13]
	v_mad_i64_i32 v[236:237], s[100:101], v234, s85, v[236:237]
	s_lshl_b32 s26, s16, 1
	v_mov_b32_e32 v238, v86
	v_mov_b32_e32 v239, 0
	v_lshl_add_u64 v[236:237], v[236:237], 0, s[26:27]
	v_lshl_add_u64 v[236:237], v[236:237], 0, v[238:239]
	s_mov_b32 s100, s86
	s_mov_b32 s101, 0
	v_lshl_add_u64 v[240:241], v[236:237], 0, s[100:101]
	global_load_dwordx2 v[220:221], v[240:241], off offset:2048
	s_lshl_b32 s26, s16, 2
	v_lshl_add_u64 v[242:243], v[82:83], 0, s[26:27]
	global_load_dwordx4 v[156:159], v[242:243], off
	global_load_dwordx4 v[160:163], v[242:243], off offset:32
	global_load_dwordx4 v[164:167], v[242:243], off offset:64
	global_load_dwordx4 v[216:219], v[242:243], off offset:96
	s_mov_b32 s100, 0x1800
	v_lshl_add_u64 v[240:241], v[236:237], 0, s[100:101]
	global_load_dwordx2 v[222:223], v[240:241], off offset:16
	global_load_dwordx2 v[224:225], v[240:241], off offset:48
	global_load_dwordx2 v[228:229], v[240:241], off offset:32
	s_add_i32 s26, s6, s24
	s_add_i32 s17, s15, s76
	s_cmpk_gt_i32 s26, 0x3ff
	s_cbranch_scc1 .Levenb_nopf
	s_and_b32 s100, s17, 0xffffffc0
	v_add_u32_e32 v152, s100, v89
	v_mov_b64_e32 v[150:151], s[12:13]
	v_mad_i64_i32 v[150:151], s[100:101], v152, s85, v[150:151]
	s_and_b32 s26, s26, 3
	s_lshl_b32 s26, s26, 8
	s_and_b32 s17, s17, 0xfc0
	v_add_u32_e32 v152, s17, v89
	v_lshl_add_u64 v[150:151], v[150:151], 0, s[26:27]
	v_ashrrev_i32_e32 v153, 31, v152
	v_lshl_add_u64 v[150:151], v[150:151], 0, v[168:169]
	v_lshlrev_b64 v[152:153], 9, v[152:153]
	s_mov_b32 s100, s86
	s_mov_b32 s101, 0
	global_load_dwordx4 v[208:211], v[150:151], off offset:3072
	global_load_dwordx4 v[212:215], v[150:151], off offset:3200
	v_lshl_add_u64 v[152:153], v[80:81], 0, v[152:153]
	v_lshl_add_u64 v[154:155], v[150:151], 0, s[100:101]
	global_load_dwordx4 v[204:207], v[152:153], off
	global_load_dwordx4 v[200:203], v[152:153], off offset:16
	global_load_dwordx4 v[192:195], v[152:153], off offset:32
	global_load_dwordx4 v[184:187], v[152:153], off offset:48
	global_load_dwordx4 v[196:199], v[154:155], off
	global_load_dwordx4 v[188:191], v[154:155], off offset:128
	global_load_dwordx4 v[176:179], v[154:155], off offset:1024
	global_load_dwordx4 v[180:183], v[154:155], off offset:1152
